# HGRN cumulative sum with batched LDS reads
# baseline (speedup 1.0000x reference)
; __device__ __forceinline__ float bf2f(bfu h) { return __uint_as_float(((unsigned)h) << 16); }
; __device__ __forceinline__ float sigmoidf_(float x) { return frcp(1.0f + fexp(-x)); }
; __device__ __forceinline__ float siluf_(float x) { return x * frcp(1.0f + fexp(-x)); }
; __device__ void hg_pre_item(const Params& p, int L, int idx) {
;     ...
;   { const int d = tid & 127, rg = tid >> 7;
;     const float lb = misc[MF_LB + li * 512 + h * 128 + d];
;     bfu hqv[16], hfv[16], hiv[16];
;     _Pragma("unroll") for (int i = 0; i < 16; ++i) {
;       const bfu* pr = buf + (R0 + rg * 16 + i) * 4608 + 1536 + h * 128 + d;
;       hqv[i] = pr[0]; hfv[i] = pr[512]; hiv[i] = pr[1024];
;     }
;     _Pragma("unroll") for (int i = 0; i < 16; ++i) {
;       const int r = rg * 16 + i;
;       float hq = bf2f(hqv[i]), hf = bf2f(hfv[i]);
;       float sg = sigmoidf_(hf);
;       float f = lb + (1.0f - lb) * sg;
;       qb[r * 136 + d] = f2bf(siluf_(hq));
;       kb[r * 136 + d] = f2bf((1.0f - lb) * sigmoidf_(-hf));
.LBB0_43:
	s_or_b64 exec, exec, s[0:1]
	s_ashr_i32 s0, s44, 8
	s_ashr_i32 s1, s0, 31
	s_lshl_b64 s[46:47], s[0:1], 12
	s_lshl_b32 s0, s44, 6
	s_and_b32 s0, s0, 0xfc0
	s_or_b32 s46, s46, s0
	s_lshl_b32 s0, s44, 1
	s_and_b32 s2, s0, 0x180
	v_and_b32_e32 v4, 0x7f, v18
	s_or_b32 s0, s2, s18
	v_or_b32_e32 v0, s0, v4
	v_readlane_b32 s0, v254, 48
	v_lshlrev_b32_e32 v0, 2, v0
	v_readlane_b32 s1, v254, 49
	v_ashrrev_i32_e32 v19, 7, v18
	v_mov_b64_e32 v[8:9], s[16:17]
	s_waitcnt lgkmcnt(0)
	v_lshl_add_u64 v[2:3], s[0:1], 0, v[0:1]
	s_mov_b32 s0, 0x120000
	v_add_co_u32_e32 v2, vcc, s0, v2
	v_lshlrev_b32_e32 v0, 1, v4
	s_nop 0
	v_addc_co_u32_e32 v3, vcc, 0, v3, vcc
	global_load_dword v40, v[2:3], off
	v_lshlrev_b32_e32 v2, 4, v19
	v_ashrrev_i32_e32 v3, 31, v2
	v_lshl_add_u64 v[6:7], s[46:47], 0, v[2:3]
	v_mad_u64_u32 v[8:9], s[0:1], v6, s89, v[8:9]
	v_readlane_b32 s0, v254, 13
	v_mad_i32_i24 v9, v7, s89, v9
	v_readlane_b32 s1, v254, 14
	s_lshl_b32 s0, s2, 1
	s_mov_b64 s[26:27], s[0:1]
	v_lshl_add_u64 v[6:7], v[8:9], 0, s[0:1]
	v_lshl_add_u64 v[6:7], v[6:7], 0, v[0:1]
	s_mov_b64 s[0:1], 0xc00
	v_lshl_add_u64 v[58:59], v[6:7], 0, s[0:1]
	s_mov_b64 s[0:1], 0x3000
	v_lshl_add_u64 v[64:65], v[6:7], 0, s[0:1]
	s_mov_b64 s[0:1], 0x5400
	v_lshl_add_u64 v[38:39], v[6:7], 0, s[0:1]
	s_mov_b64 s[0:1], 0x7800
	v_lshl_add_u64 v[36:37], v[6:7], 0, s[0:1]
	s_mov_b64 s[0:1], 0x9c00
	v_lshl_add_u64 v[34:35], v[6:7], 0, s[0:1]
	s_mov_b64 s[0:1], 0xc000
	v_lshl_add_u64 v[32:33], v[6:7], 0, s[0:1]
	s_mov_b64 s[0:1], 0xe400
	global_load_ushort v56, v[58:59], off offset:2048
	global_load_ushort v55, v[64:65], off offset:2048
	global_load_ushort v54, v[38:39], off offset:2048
	global_load_ushort v52, v[34:35], off offset:2048
	global_load_ushort v51, v[32:33], off offset:2048
	v_lshl_add_u64 v[30:31], v[6:7], 0, s[0:1]
	s_mov_b64 s[0:1], 0x10800
	global_load_ushort v58, v[58:59], off offset:1024
	v_lshl_add_u64 v[28:29], v[6:7], 0, s[0:1]
	s_mov_b64 s[0:1], 0x12c00
	v_lshl_add_u64 v[26:27], v[6:7], 0, s[0:1]
	s_mov_b64 s[0:1], 0x15000
	v_lshl_add_u64 v[24:25], v[6:7], 0, s[0:1]
	s_mov_b64 s[0:1], 0x17400
	v_lshl_add_u64 v[22:23], v[6:7], 0, s[0:1]
	s_mov_b64 s[0:1], 0x19800
	v_lshl_add_u64 v[16:17], v[6:7], 0, s[0:1]
	s_mov_b64 s[0:1], 0x1bc00
	v_lshl_add_u64 v[14:15], v[6:7], 0, s[0:1]
	s_mov_b64 s[0:1], 0x1e000
	v_lshl_add_u64 v[12:13], v[6:7], 0, s[0:1]
	s_mov_b64 s[0:1], 0x20400
	v_lshl_add_u64 v[10:11], v[6:7], 0, s[0:1]
	s_mov_b64 s[0:1], 0x22800
	v_lshl_add_u64 v[8:9], v[6:7], 0, s[0:1]
	global_load_ushort v47, v[24:25], off offset:2048
	global_load_ushort v46, v[22:23], off offset:2048
	global_load_ushort v45, v[16:17], off offset:2048
	global_load_ushort v44, v[14:15], off offset:2048
	global_load_ushort v43, v[12:13], off offset:2048
	global_load_ushort v42, v[10:11], off offset:2048
	global_load_ushort v3, v[8:9], off offset:2048
	global_load_ushort v60, v[6:7], off offset:3072
	s_movk_i32 s0, 0x880
	v_add_u32_e32 v20, 0, v5
	global_load_ushort v53, v[36:37], off offset:2048
	global_load_ushort v50, v[30:31], off offset:2048
	global_load_ushort v49, v[28:29], off offset:2048
	global_load_ushort v48, v[26:27], off offset:2048
	v_lshl_add_u32 v0, v4, 2, v20
	v_add_u32_e32 v21, 0x10c00, v20
	v_mul_u32_u24_e32 v57, 0x90, v4
	s_waitcnt vmcnt(0)
	v_sub_f32_e32 v41, 1.0, v40
	s_waitcnt vmcnt(12)
	v_lshlrev_b32_e32 v63, 16, v58
	v_mul_f32_e32 v58, 0xbfb8aa3b, v63
	v_exp_f32_e32 v58, v58
	s_waitcnt vmcnt(4)
	v_lshlrev_b32_e32 v61, 16, v60
	v_add_f32_e32 v58, 1.0, v58
	v_rcp_f32_e32 v58, v58
	s_nop 0
	v_fma_f32 v60, v41, v58, v40
	v_mul_f32_e32 v58, 0xbfb8aa3b, v61
	v_exp_f32_e32 v58, v58
	s_nop 0
	v_add_f32_e32 v58, 1.0, v58
	v_rcp_f32_e32 v58, v58
	s_nop 0
	v_mul_f32_e32 v58, v58, v61
	v_bfe_u32 v59, v58, 16, 1
	v_add3_u32 v66, v58, v59, s72
	v_mul_lo_u32 v58, v19, s0
	v_or_b32_e32 v58, v58, v4
	s_movk_i32 s0, 0x3000
	v_lshl_add_u32 v62, v58, 1, v20
	v_add_co_u32_e32 v58, vcc, s0, v6
	s_movk_i32 s0, 0x5000
	s_nop 0
	v_addc_co_u32_e32 v59, vcc, 0, v7, vcc
	global_load_ushort v61, v[58:59], off
	s_nop 0
	global_load_ushort v59, v[64:65], off offset:1024
	v_add_co_u32_e32 v64, vcc, s0, v6
	s_movk_i32 s0, 0x7000
	s_nop 0
	v_addc_co_u32_e32 v65, vcc, 0, v7, vcc
	global_load_ushort v58, v[64:65], off offset:1024
	s_nop 0
	global_load_ushort v39, v[38:39], off offset:1024
	v_add_co_u32_e32 v64, vcc, s0, v6
	s_mov_b32 s0, 0x9000
	s_nop 0
	v_addc_co_u32_e32 v65, vcc, 0, v7, vcc
	global_load_ushort v64, v[64:65], off offset:2048
	s_nop 0
	global_load_ushort v65, v[36:37], off offset:1024
	v_add_co_u32_e32 v36, vcc, s0, v6
	s_mov_b32 s0, 0xc000
	s_nop 0
	v_addc_co_u32_e32 v37, vcc, 0, v7, vcc
	global_load_ushort v37, v[36:37], off offset:3072
	s_nop 0
	global_load_ushort v38, v[34:35], off offset:1024
	v_add_co_u32_e32 v34, vcc, s0, v6
	s_mov_b32 s0, 0xe000
	s_nop 0
	v_addc_co_u32_e32 v35, vcc, 0, v7, vcc
	global_load_ushort v34, v[34:35], off
	s_nop 0
	global_load_ushort v35, v[32:33], off offset:1024
	v_add_co_u32_e32 v32, vcc, s0, v6
	s_mov_b32 s0, 0x10000
	s_nop 0
	v_addc_co_u32_e32 v33, vcc, 0, v7, vcc
	global_load_ushort v32, v[32:33], off offset:1024
	s_nop 0
	global_load_ushort v36, v[30:31], off offset:1024
	v_add_co_u32_e32 v30, vcc, s0, v6
	s_mov_b32 s0, 0x12000
	s_nop 0
	v_addc_co_u32_e32 v31, vcc, 0, v7, vcc
	global_load_ushort v31, v[30:31], off offset:2048
	s_nop 0
	global_load_ushort v33, v[28:29], off offset:1024
	v_add_co_u32_e32 v28, vcc, s0, v6
	s_mov_b32 s0, 0x15000
	s_nop 0
	v_addc_co_u32_e32 v29, vcc, 0, v7, vcc
	global_load_ushort v29, v[28:29], off offset:3072
	s_nop 0
	global_load_ushort v30, v[26:27], off offset:1024
	v_add_co_u32_e32 v26, vcc, s0, v6
; __device__ __forceinline__ float bf2f(bfu h) { return __uint_as_float(((unsigned)h) << 16); }
; __device__ __forceinline__ float sigmoidf_(float x) { return frcp(1.0f + fexp(-x)); }
; __device__ __forceinline__ float siluf_(float x) { return x * frcp(1.0f + fexp(-x)); }
; __device__ void hg_pre_item(const Params& p, int L, int idx) {
;     ...
;     _Pragma("unroll") for (int i = 0; i < 16; ++i) {
;       const int r = rg * 16 + i;
;       float hq = bf2f(hqv[i]), hf = bf2f(hfv[i]);
;       float sg = sigmoidf_(hf);
;       float f = lb + (1.0f - lb) * sg;
;       qb[r * 136 + d] = f2bf(siluf_(hq));
;       kb[r * 136 + d] = f2bf((1.0f - lb) * sigmoidf_(-hf));
;       bs[r * 132 + d] = __builtin_amdgcn_logf(f);
;       vT[d * 72 + r] = hiv[i];
;     }
	s_mov_b32 s0, 0x17000
	s_nop 0
	v_addc_co_u32_e32 v27, vcc, 0, v7, vcc
	global_load_ushort v27, v[26:27], off
	s_nop 0
	global_load_ushort v28, v[24:25], off offset:1024
	v_add_co_u32_e32 v24, vcc, s0, v6
	s_mov_b32 s0, 0x19000
	s_nop 0
	v_addc_co_u32_e32 v25, vcc, 0, v7, vcc
	global_load_ushort v25, v[24:25], off offset:1024
	s_nop 0
	global_load_ushort v26, v[22:23], off offset:1024
	v_add_co_u32_e32 v22, vcc, s0, v6
	s_mov_b32 s0, 0x1b000
	s_nop 0
	v_addc_co_u32_e32 v23, vcc, 0, v7, vcc
	global_load_ushort v23, v[22:23], off offset:2048
	s_nop 0
	global_load_ushort v24, v[16:17], off offset:1024
	v_add_co_u32_e32 v16, vcc, s0, v6
	s_mov_b32 s0, 0x1e000
	s_nop 0
	v_addc_co_u32_e32 v17, vcc, 0, v7, vcc
	global_load_ushort v17, v[16:17], off offset:3072
	s_nop 0
	global_load_ushort v22, v[14:15], off offset:1024
	v_add_co_u32_e32 v14, vcc, s0, v6
	s_mov_b32 s0, 0x20000
	s_nop 0
	v_addc_co_u32_e32 v15, vcc, 0, v7, vcc
	global_load_ushort v15, v[14:15], off
	s_nop 0
	global_load_ushort v16, v[12:13], off offset:1024
	v_add_co_u32_e32 v12, vcc, s0, v6
	s_mov_b32 s0, 0x22000
	s_nop 0
	v_addc_co_u32_e32 v13, vcc, 0, v7, vcc
	v_add_co_u32_e32 v6, vcc, s0, v6
	global_load_ushort v12, v[12:13], off offset:1024
	s_nop 0
	global_load_ushort v13, v[10:11], off offset:1024
	v_addc_co_u32_e32 v7, vcc, 0, v7, vcc
	global_load_ushort v10, v[6:7], off offset:2048
	global_load_ushort v11, v[8:9], off offset:1024
	v_mul_f32_e32 v6, 0x3fb8aa3b, v63
	v_exp_f32_e32 v6, v6
	s_movk_i32 s0, 0x2100
	v_mul_lo_u32 v8, v19, s0
	ds_write_b16_d16_hi v62, v66 offset:33792
	v_add_f32_e32 v6, 1.0, v6
	v_rcp_f32_e32 v6, v6
	s_movk_i32 s0, 0x88
	s_waitcnt vmcnt(26)
	v_lshlrev_b32_e32 v39, 16, v39
	v_mul_f32_e32 v6, v41, v6
	v_bfe_u32 v7, v6, 16, 1
	v_add3_u32 v6, v6, v7, s72
	ds_write_b16_d16_hi v62, v6 offset:51200
	v_log_f32_e32 v6, v60
	v_add_u32_e32 v7, v0, v8
	s_waitcnt vmcnt(23)
	v_lshlrev_b32_e32 v37, 16, v37
	s_waitcnt vmcnt(22)
	v_lshlrev_b32_e32 v38, 16, v38
	ds_write_b32 v7, v6
	v_lshlrev_b32_e32 v6, 5, v19
	v_add3_u32 v9, v21, v57, v6
	v_lshlrev_b32_e32 v57, 16, v59
	v_mul_f32_e32 v7, 0xbfb8aa3b, v57
	v_exp_f32_e32 v7, v7
	v_lshlrev_b32_e32 v6, 16, v61
	ds_write_b16 v9, v56
	v_or_b32_e32 v56, 1, v2
	v_add_f32_e32 v7, 1.0, v7
	v_rcp_f32_e32 v7, v7
	s_waitcnt vmcnt(19)
	v_lshlrev_b32_e32 v32, 16, v32
	v_fma_f32 v59, v41, v7, v40
	v_mul_f32_e32 v7, 0xbfb8aa3b, v6
	v_exp_f32_e32 v7, v7
	s_waitcnt vmcnt(15)
	v_lshlrev_b32_e32 v29, 16, v29
	v_add_f32_e32 v7, 1.0, v7
	v_rcp_f32_e32 v7, v7
	s_waitcnt vmcnt(14)
	v_lshlrev_b32_e32 v30, 16, v30
	v_mul_f32_e32 v6, v7, v6
	v_bfe_u32 v7, v6, 16, 1
	v_add3_u32 v60, v6, v7, s72
	v_mad_u64_u32 v[6:7], s[0:1], v56, s0, v[4:5]
	v_lshl_add_u32 v14, v6, 1, v20
	v_mul_f32_e32 v6, 0x3fb8aa3b, v57
	v_exp_f32_e32 v6, v6
	s_movk_i32 s0, 0x210
	ds_write_b16_d16_hi v14, v60 offset:33792
	v_log_f32_e32 v57, v59
	v_add_f32_e32 v6, 1.0, v6
	v_rcp_f32_e32 v6, v6
	s_waitcnt vmcnt(11)
	v_lshlrev_b32_e32 v25, 16, v25
	s_waitcnt vmcnt(10)
	v_lshlrev_b32_e32 v26, 16, v26
	v_mul_f32_e32 v6, v41, v6
	v_bfe_u32 v7, v6, 16, 1
	v_add3_u32 v6, v6, v7, s72
	ds_write_b16_d16_hi v14, v6 offset:51200
	v_mad_u64_u32 v[6:7], s[0:1], v56, s0, v[0:1]
	v_lshlrev_b32_e32 v7, 16, v58
	v_mul_f32_e32 v56, 0xbfb8aa3b, v7
	v_exp_f32_e32 v56, v56
	ds_write_b16 v9, v55 offset:2
	v_mul_f32_e32 v55, 0xbfb8aa3b, v39
	v_exp_f32_e32 v55, v55
	v_add_f32_e32 v56, 1.0, v56
	v_rcp_f32_e32 v56, v56
	s_waitcnt vmcnt(7)
	v_lshlrev_b32_e32 v17, 16, v17
	v_add_f32_e32 v55, 1.0, v55
	v_rcp_f32_e32 v55, v55
	v_mul_f32_e32 v7, v56, v7
	v_bfe_u32 v56, v7, 16, 1
	v_add3_u32 v7, v7, v56, s72
	ds_write_b16_d16_hi v14, v7 offset:34064
	v_mul_f32_e32 v7, 0x3fb8aa3b, v39
	v_exp_f32_e32 v7, v7
	v_fma_f32 v55, v41, v55, v40
	s_waitcnt vmcnt(6)
	v_lshlrev_b32_e32 v22, 16, v22
	s_waitcnt vmcnt(3)
	v_lshlrev_b32_e32 v12, 16, v12
	v_add_f32_e32 v7, 1.0, v7
	v_rcp_f32_e32 v7, v7
	s_waitcnt vmcnt(2)
	v_lshlrev_b32_e32 v13, 16, v13
	s_movk_i32 s0, 0x80
	v_cmp_gt_i32_e32 vcc, s0, v18
	v_mul_f32_e32 v7, v41, v7
	v_bfe_u32 v39, v7, 16, 1
	v_add3_u32 v7, v7, v39, s72
	ds_write_b16_d16_hi v14, v7 offset:51472
	v_log_f32_e32 v7, v55
	ds_write2_b32 v6, v57, v7 offset1:132
	ds_write_b16 v9, v54 offset:4
	v_lshlrev_b32_e32 v7, 16, v64
	v_mul_f32_e32 v55, 0xbfb8aa3b, v7
	v_exp_f32_e32 v55, v55
	v_lshlrev_b32_e32 v39, 16, v65
	v_mul_f32_e32 v54, 0xbfb8aa3b, v39
	v_exp_f32_e32 v54, v54
	v_add_f32_e32 v55, 1.0, v55
	v_rcp_f32_e32 v55, v55
	v_add_f32_e32 v54, 1.0, v54
	v_rcp_f32_e32 v54, v54
	v_mul_f32_e32 v7, v55, v7
	v_bfe_u32 v55, v7, 16, 1
	v_add3_u32 v7, v7, v55, s72
	ds_write_b16_d16_hi v14, v7 offset:34336
	v_mul_f32_e32 v7, 0x3fb8aa3b, v39
	v_exp_f32_e32 v7, v7
	v_fma_f32 v54, v41, v54, v40
	v_add_f32_e32 v7, 1.0, v7
	v_rcp_f32_e32 v7, v7
	s_nop 0
	v_mul_f32_e32 v7, v41, v7
	v_bfe_u32 v39, v7, 16, 1
	v_add3_u32 v7, v7, v39, s72
	ds_write_b16_d16_hi v14, v7 offset:51744
	ds_write_b16 v9, v53 offset:6
	v_mul_f32_e32 v53, 0xbfb8aa3b, v37
	v_exp_f32_e32 v53, v53
	v_mul_f32_e32 v39, 0xbfb8aa3b, v38
	v_exp_f32_e32 v39, v39
	v_log_f32_e32 v7, v54
	v_add_f32_e32 v53, 1.0, v53
	v_rcp_f32_e32 v53, v53
	v_add_f32_e32 v39, 1.0, v39
	v_rcp_f32_e32 v39, v39
	v_mul_f32_e32 v37, v53, v37
	v_bfe_u32 v53, v37, 16, 1
	v_add3_u32 v37, v37, v53, s72
	ds_write_b16_d16_hi v14, v37 offset:34608
	v_mul_f32_e32 v37, 0x3fb8aa3b, v38
	v_exp_f32_e32 v37, v37
	v_fma_f32 v39, v41, v39, v40
	v_add_f32_e32 v37, 1.0, v37
	v_rcp_f32_e32 v37, v37
	s_nop 0
	v_mul_f32_e32 v37, v41, v37
	v_bfe_u32 v38, v37, 16, 1
	v_add3_u32 v37, v37, v38, s72
	ds_write_b16_d16_hi v14, v37 offset:52016
	v_log_f32_e32 v37, v39
	v_add_u32_e32 v38, 0x400, v6
; __device__ __forceinline__ float bf2f(bfu h) { return __uint_as_float(((unsigned)h) << 16); }
; __device__ __forceinline__ float sigmoidf_(float x) { return frcp(1.0f + fexp(-x)); }
; __device__ __forceinline__ float siluf_(float x) { return x * frcp(1.0f + fexp(-x)); }
; __device__ void hg_pre_item(const Params& p, int L, int idx) {
;     ...
;     _Pragma("unroll") for (int i = 0; i < 16; ++i) {
;       const int r = rg * 16 + i;
;       float hq = bf2f(hqv[i]), hf = bf2f(hfv[i]);
;       float sg = sigmoidf_(hf);
;       float f = lb + (1.0f - lb) * sg;
;       qb[r * 136 + d] = f2bf(siluf_(hq));
;       kb[r * 136 + d] = f2bf((1.0f - lb) * sigmoidf_(-hf));
;       bs[r * 132 + d] = __builtin_amdgcn_logf(f);
;       vT[d * 72 + r] = hiv[i];
;     }
	ds_write2_b32 v38, v7, v37 offset0:8 offset1:140
	ds_write_b16 v9, v52 offset:8
	v_lshlrev_b32_e32 v7, 16, v34
	v_mul_f32_e32 v37, 0xbfb8aa3b, v7
	v_exp_f32_e32 v37, v37
	v_lshlrev_b32_e32 v34, 16, v35
	v_mul_f32_e32 v35, 0xbfb8aa3b, v34
	v_exp_f32_e32 v35, v35
	v_add_f32_e32 v37, 1.0, v37
	v_rcp_f32_e32 v37, v37
	v_add_f32_e32 v35, 1.0, v35
	v_rcp_f32_e32 v35, v35
	v_mul_f32_e32 v7, v37, v7
	v_bfe_u32 v37, v7, 16, 1
	v_add3_u32 v7, v7, v37, s72
	ds_write_b16_d16_hi v14, v7 offset:34880
	v_mul_f32_e32 v7, 0x3fb8aa3b, v34
	v_exp_f32_e32 v7, v7
	v_fma_f32 v35, v41, v35, v40
	v_add_f32_e32 v7, 1.0, v7
	v_rcp_f32_e32 v7, v7
	s_nop 0
	v_mul_f32_e32 v7, v41, v7
	v_bfe_u32 v34, v7, 16, 1
	v_add3_u32 v7, v7, v34, s72
	v_lshlrev_b32_e32 v34, 16, v36
	v_mul_f32_e32 v36, 0xbfb8aa3b, v32
	v_exp_f32_e32 v36, v36
	ds_write_b16_d16_hi v14, v7 offset:52288
	ds_write_b16 v9, v51 offset:10
	v_log_f32_e32 v7, v35
	v_add_f32_e32 v36, 1.0, v36
	v_rcp_f32_e32 v36, v36
	v_mul_f32_e32 v35, 0xbfb8aa3b, v34
	v_exp_f32_e32 v35, v35
	v_mul_f32_e32 v32, v36, v32
	v_bfe_u32 v36, v32, 16, 1
	v_add3_u32 v32, v32, v36, s72
	ds_write_b16_d16_hi v14, v32 offset:35152
	v_mul_f32_e32 v32, 0x3fb8aa3b, v34
	v_exp_f32_e32 v32, v32
	v_add_f32_e32 v35, 1.0, v35
	v_rcp_f32_e32 v35, v35
	v_add_f32_e32 v32, 1.0, v32
	v_rcp_f32_e32 v32, v32
	v_fma_f32 v35, v41, v35, v40
	v_mul_f32_e32 v32, v41, v32
	v_bfe_u32 v34, v32, 16, 1
	v_add3_u32 v32, v32, v34, s72
	ds_write_b16_d16_hi v14, v32 offset:52560
	v_log_f32_e32 v32, v35
	v_add_u32_e32 v34, 0x800, v6
	ds_write2_b32 v34, v7, v32 offset0:16 offset1:148
	ds_write_b16 v9, v50 offset:12
	v_lshlrev_b32_e32 v7, 16, v31
	v_lshlrev_b32_e32 v31, 16, v33
	v_mul_f32_e32 v33, 0xbfb8aa3b, v7
	v_exp_f32_e32 v33, v33
	v_mul_f32_e32 v32, 0xbfb8aa3b, v31
	v_exp_f32_e32 v32, v32
	v_add_f32_e32 v33, 1.0, v33
	v_rcp_f32_e32 v33, v33
	v_add_f32_e32 v32, 1.0, v32
	v_rcp_f32_e32 v32, v32
	v_mul_f32_e32 v7, v33, v7
	v_bfe_u32 v33, v7, 16, 1
	v_add3_u32 v7, v7, v33, s72
	ds_write_b16_d16_hi v14, v7 offset:35424
	v_mul_f32_e32 v7, 0x3fb8aa3b, v31
	v_exp_f32_e32 v7, v7
	v_fma_f32 v32, v41, v32, v40
	v_add_f32_e32 v7, 1.0, v7
	v_rcp_f32_e32 v7, v7
	s_nop 0
	v_mul_f32_e32 v7, v41, v7
	v_bfe_u32 v31, v7, 16, 1
	v_add3_u32 v7, v7, v31, s72
	ds_write_b16_d16_hi v14, v7 offset:52832
	v_log_f32_e32 v7, v32
	v_mul_f32_e32 v32, 0xbfb8aa3b, v29
	v_exp_f32_e32 v32, v32
	ds_write_b16 v9, v49 offset:14
	v_mul_f32_e32 v31, 0xbfb8aa3b, v30
	v_exp_f32_e32 v31, v31
	v_add_f32_e32 v32, 1.0, v32
	v_rcp_f32_e32 v32, v32
	v_add_f32_e32 v31, 1.0, v31
	v_rcp_f32_e32 v31, v31
	v_mul_f32_e32 v29, v32, v29
	v_bfe_u32 v32, v29, 16, 1
	v_add3_u32 v29, v29, v32, s72
	ds_write_b16_d16_hi v14, v29 offset:35696
	v_mul_f32_e32 v29, 0x3fb8aa3b, v30
	v_exp_f32_e32 v29, v29
	v_fma_f32 v31, v41, v31, v40
	v_add_f32_e32 v29, 1.0, v29
	v_rcp_f32_e32 v29, v29
	s_nop 0
	v_mul_f32_e32 v29, v41, v29
	v_bfe_u32 v30, v29, 16, 1
	v_add3_u32 v29, v29, v30, s72
	ds_write_b16_d16_hi v14, v29 offset:53104
	v_log_f32_e32 v29, v31
	v_add_u32_e32 v30, 0xc00, v6
	ds_write2_b32 v30, v7, v29 offset0:24 offset1:156
	ds_write_b16 v9, v48 offset:16
	v_lshlrev_b32_e32 v7, 16, v27
	v_mul_f32_e32 v29, 0xbfb8aa3b, v7
	v_exp_f32_e32 v29, v29
	v_lshlrev_b32_e32 v27, 16, v28
	v_mul_f32_e32 v28, 0xbfb8aa3b, v27
	v_exp_f32_e32 v28, v28
	v_add_f32_e32 v29, 1.0, v29
	v_rcp_f32_e32 v29, v29
	v_add_f32_e32 v28, 1.0, v28
	v_rcp_f32_e32 v28, v28
	v_mul_f32_e32 v7, v29, v7
	v_bfe_u32 v29, v7, 16, 1
	v_add3_u32 v7, v7, v29, s72
	ds_write_b16_d16_hi v14, v7 offset:35968
	v_mul_f32_e32 v7, 0x3fb8aa3b, v27
	v_exp_f32_e32 v7, v7
	v_fma_f32 v28, v41, v28, v40
	v_add_f32_e32 v7, 1.0, v7
	v_rcp_f32_e32 v7, v7
	s_nop 0
	v_mul_f32_e32 v7, v41, v7
	v_bfe_u32 v27, v7, 16, 1
	v_add3_u32 v7, v7, v27, s72
	ds_write_b16_d16_hi v14, v7 offset:53376
	v_log_f32_e32 v7, v28
	v_mul_f32_e32 v28, 0xbfb8aa3b, v25
	v_exp_f32_e32 v28, v28
	ds_write_b16 v9, v47 offset:18
	v_mul_f32_e32 v27, 0xbfb8aa3b, v26
	v_exp_f32_e32 v27, v27
	v_add_f32_e32 v28, 1.0, v28
	v_rcp_f32_e32 v28, v28
	v_add_f32_e32 v27, 1.0, v27
	v_rcp_f32_e32 v27, v27
	v_mul_f32_e32 v25, v28, v25
	v_bfe_u32 v28, v25, 16, 1
	v_add3_u32 v25, v25, v28, s72
	ds_write_b16_d16_hi v14, v25 offset:36240
	v_mul_f32_e32 v25, 0x3fb8aa3b, v26
	v_exp_f32_e32 v25, v25
	v_fma_f32 v27, v41, v27, v40
	v_add_f32_e32 v25, 1.0, v25
	v_rcp_f32_e32 v25, v25
	s_nop 0
	v_mul_f32_e32 v25, v41, v25
	v_bfe_u32 v26, v25, 16, 1
	v_add3_u32 v25, v25, v26, s72
	ds_write_b16_d16_hi v14, v25 offset:53648
	v_log_f32_e32 v25, v27
	v_add_u32_e32 v26, 0x1000, v6
	ds_write2_b32 v26, v7, v25 offset0:32 offset1:164
	ds_write_b16 v9, v46 offset:20
	v_lshlrev_b32_e32 v7, 16, v23
	v_mul_f32_e32 v25, 0xbfb8aa3b, v7
	v_exp_f32_e32 v25, v25
	v_lshlrev_b32_e32 v23, 16, v24
	v_mul_f32_e32 v24, 0xbfb8aa3b, v23
	v_exp_f32_e32 v24, v24
	v_add_f32_e32 v25, 1.0, v25
	v_rcp_f32_e32 v25, v25
	v_add_f32_e32 v24, 1.0, v24
	v_rcp_f32_e32 v24, v24
	v_mul_f32_e32 v7, v25, v7
	v_bfe_u32 v25, v7, 16, 1
	v_add3_u32 v7, v7, v25, s72
	ds_write_b16_d16_hi v14, v7 offset:36512
	v_mul_f32_e32 v7, 0x3fb8aa3b, v23
	v_exp_f32_e32 v7, v7
	v_fma_f32 v24, v41, v24, v40
	v_add_f32_e32 v7, 1.0, v7
	v_rcp_f32_e32 v7, v7
	s_nop 0
	v_mul_f32_e32 v7, v41, v7
	v_bfe_u32 v23, v7, 16, 1
	v_add3_u32 v7, v7, v23, s72
	ds_write_b16_d16_hi v14, v7 offset:53920
	v_log_f32_e32 v7, v24
	v_mul_f32_e32 v24, 0xbfb8aa3b, v17
	v_exp_f32_e32 v24, v24
	ds_write_b16 v9, v45 offset:22
	v_mul_f32_e32 v23, 0xbfb8aa3b, v22
	v_exp_f32_e32 v23, v23
	v_add_f32_e32 v24, 1.0, v24
	v_rcp_f32_e32 v24, v24
	v_add_f32_e32 v23, 1.0, v23
	v_rcp_f32_e32 v23, v23
	v_mul_f32_e32 v17, v24, v17
; __device__ __forceinline__ float bf2f(bfu h) { return __uint_as_float(((unsigned)h) << 16); }
; __device__ __forceinline__ float sigmoidf_(float x) { return frcp(1.0f + fexp(-x)); }
; __device__ __forceinline__ float siluf_(float x) { return x * frcp(1.0f + fexp(-x)); }
; __device__ void hg_pre_item(const Params& p, int L, int idx) {
;     ...
;     _Pragma("unroll") for (int i = 0; i < 16; ++i) {
;       const int r = rg * 16 + i;
;       float hq = bf2f(hqv[i]), hf = bf2f(hfv[i]);
;       float sg = sigmoidf_(hf);
;       float f = lb + (1.0f - lb) * sg;
;       qb[r * 136 + d] = f2bf(siluf_(hq));
;       kb[r * 136 + d] = f2bf((1.0f - lb) * sigmoidf_(-hf));
;       bs[r * 132 + d] = __builtin_amdgcn_logf(f);
;       vT[d * 72 + r] = hiv[i];
;     }
;   }
;   __syncthreads();
;   if (tid < 128) { float a = 0.f; for (int r = 0; r < 64; ++r) { a += bs[r * 132 + tid]; bs[r * 132 + tid] = a; } }
	v_bfe_u32 v24, v17, 16, 1
	v_add3_u32 v17, v17, v24, s72
	ds_write_b16_d16_hi v14, v17 offset:36784
	v_mul_f32_e32 v17, 0x3fb8aa3b, v22
	v_exp_f32_e32 v17, v17
	v_fma_f32 v23, v41, v23, v40
	v_add_f32_e32 v17, 1.0, v17
	v_rcp_f32_e32 v17, v17
	s_nop 0
	v_mul_f32_e32 v17, v41, v17
	v_bfe_u32 v22, v17, 16, 1
	v_add3_u32 v17, v17, v22, s72
	ds_write_b16_d16_hi v14, v17 offset:54192
	v_log_f32_e32 v17, v23
	v_add_u32_e32 v22, 0x1400, v6
	ds_write2_b32 v22, v7, v17 offset0:40 offset1:172
	ds_write_b16 v9, v44 offset:24
	v_lshlrev_b32_e32 v7, 16, v15
	v_mul_f32_e32 v17, 0xbfb8aa3b, v7
	v_exp_f32_e32 v17, v17
	v_lshlrev_b32_e32 v15, 16, v16
	v_mul_f32_e32 v16, 0xbfb8aa3b, v15
	v_exp_f32_e32 v16, v16
	v_add_f32_e32 v17, 1.0, v17
	v_rcp_f32_e32 v17, v17
	v_add_f32_e32 v16, 1.0, v16
	v_rcp_f32_e32 v16, v16
	v_mul_f32_e32 v7, v17, v7
	v_bfe_u32 v17, v7, 16, 1
	v_add3_u32 v7, v7, v17, s72
	ds_write_b16_d16_hi v14, v7 offset:37056
	v_mul_f32_e32 v7, 0x3fb8aa3b, v15
	v_exp_f32_e32 v7, v7
	v_fma_f32 v16, v41, v16, v40
	v_add_f32_e32 v7, 1.0, v7
	v_rcp_f32_e32 v7, v7
	s_nop 0
	v_mul_f32_e32 v7, v41, v7
	v_bfe_u32 v15, v7, 16, 1
	v_add3_u32 v7, v7, v15, s72
	ds_write_b16_d16_hi v14, v7 offset:54464
	v_log_f32_e32 v7, v16
	v_mul_f32_e32 v16, 0xbfb8aa3b, v12
	v_exp_f32_e32 v16, v16
	ds_write_b16 v9, v43 offset:26
	v_mul_f32_e32 v15, 0xbfb8aa3b, v13
	v_exp_f32_e32 v15, v15
	v_add_f32_e32 v16, 1.0, v16
	v_rcp_f32_e32 v16, v16
	v_add_f32_e32 v15, 1.0, v15
	v_rcp_f32_e32 v15, v15
	v_mul_f32_e32 v12, v16, v12
	v_bfe_u32 v16, v12, 16, 1
	v_add3_u32 v12, v12, v16, s72
	ds_write_b16_d16_hi v14, v12 offset:37328
	v_mul_f32_e32 v12, 0x3fb8aa3b, v13
	v_exp_f32_e32 v12, v12
	v_fma_f32 v15, v41, v15, v40
	v_add_f32_e32 v12, 1.0, v12
	v_rcp_f32_e32 v12, v12
	s_nop 0
	v_mul_f32_e32 v12, v41, v12
	v_bfe_u32 v13, v12, 16, 1
	v_add3_u32 v12, v12, v13, s72
	ds_write_b16_d16_hi v14, v12 offset:54736
	v_log_f32_e32 v12, v15
	v_add_u32_e32 v13, 0x1800, v6
	ds_write2_b32 v13, v7, v12 offset0:48 offset1:180
	ds_write_b16 v9, v42 offset:28
	s_waitcnt vmcnt(1)
	v_lshlrev_b32_e32 v7, 16, v10
	s_waitcnt vmcnt(0)
	v_lshlrev_b32_e32 v10, 16, v11
	v_mul_f32_e32 v11, 0xbfb8aa3b, v10
	v_exp_f32_e32 v11, v11
	s_nop 0
	v_add_f32_e32 v11, 1.0, v11
	v_rcp_f32_e32 v11, v11
	s_nop 0
	v_fmac_f32_e32 v40, v41, v11
	v_mul_f32_e32 v11, 0xbfb8aa3b, v7
	v_exp_f32_e32 v11, v11
	s_nop 0
	v_add_f32_e32 v11, 1.0, v11
	v_rcp_f32_e32 v11, v11
	s_nop 0
	v_mul_f32_e32 v7, v11, v7
	v_bfe_u32 v11, v7, 16, 1
	v_add3_u32 v7, v7, v11, s72
	ds_write_b16_d16_hi v14, v7 offset:37600
	v_mul_f32_e32 v7, 0x3fb8aa3b, v10
	v_exp_f32_e32 v7, v7
	s_nop 0
	v_add_f32_e32 v7, 1.0, v7
	v_rcp_f32_e32 v7, v7
	s_nop 0
	v_mul_f32_e32 v7, v41, v7
	v_bfe_u32 v10, v7, 16, 1
	v_add3_u32 v7, v7, v10, s72
	ds_write_b16_d16_hi v14, v7 offset:55008
	v_log_f32_e32 v7, v40
	ds_write_b32 v6, v7 offset:7392
	ds_write_b16 v9, v3 offset:30
	v_lshl_add_u32 v3, v18, 2, v20
	s_waitcnt lgkmcnt(0)
	s_barrier
	s_and_saveexec_b64 s[0:1], vcc
	s_cbranch_execz .LBB0_45
; __device__ void hg_pre_item(const Params& p, int L, int idx) {
;     ...
;   __syncthreads();
;   if (tid < 128) { float a = 0.f; for (int r = 0; r < 64; ++r) { a += bs[r * 132 + tid]; bs[r * 132 + tid] = a; } }
;   __syncthreads();
	v_mov_b32_e32 v176, v3
	ds_read2_b32 v[112:113], v176 offset1:132
	v_add_u32_e32 v176, 0x420, v176
	ds_read2_b32 v[114:115], v176 offset1:132
	v_add_u32_e32 v176, 0x420, v176
	ds_read2_b32 v[116:117], v176 offset1:132
	v_add_u32_e32 v176, 0x420, v176
	ds_read2_b32 v[118:119], v176 offset1:132
	v_add_u32_e32 v176, 0x420, v176
	ds_read2_b32 v[120:121], v176 offset1:132
	v_add_u32_e32 v176, 0x420, v176
	ds_read2_b32 v[122:123], v176 offset1:132
	v_add_u32_e32 v176, 0x420, v176
	ds_read2_b32 v[124:125], v176 offset1:132
	v_add_u32_e32 v176, 0x420, v176
	ds_read2_b32 v[126:127], v176 offset1:132
	v_add_u32_e32 v176, 0x420, v176
	ds_read2_b32 v[128:129], v176 offset1:132
	v_add_u32_e32 v176, 0x420, v176
	ds_read2_b32 v[130:131], v176 offset1:132
	v_add_u32_e32 v176, 0x420, v176
	ds_read2_b32 v[132:133], v176 offset1:132
	v_add_u32_e32 v176, 0x420, v176
	ds_read2_b32 v[134:135], v176 offset1:132
	v_add_u32_e32 v176, 0x420, v176
	ds_read2_b32 v[136:137], v176 offset1:132
	v_add_u32_e32 v176, 0x420, v176
	ds_read2_b32 v[138:139], v176 offset1:132
	v_add_u32_e32 v176, 0x420, v176
	ds_read2_b32 v[140:141], v176 offset1:132
	v_add_u32_e32 v176, 0x420, v176
	s_waitcnt lgkmcnt(0)
	ds_read2_b32 v[142:143], v176 offset1:132
	v_add_u32_e32 v176, 0x420, v176
	ds_read2_b32 v[144:145], v176 offset1:132
	v_add_u32_e32 v176, 0x420, v176
	ds_read2_b32 v[146:147], v176 offset1:132
	v_add_u32_e32 v176, 0x420, v176
	ds_read2_b32 v[148:149], v176 offset1:132
	v_add_u32_e32 v176, 0x420, v176
	ds_read2_b32 v[150:151], v176 offset1:132
	v_add_u32_e32 v176, 0x420, v176
	ds_read2_b32 v[152:153], v176 offset1:132
	v_add_u32_e32 v176, 0x420, v176
	ds_read2_b32 v[154:155], v176 offset1:132
	v_add_u32_e32 v176, 0x420, v176
	ds_read2_b32 v[156:157], v176 offset1:132
	v_add_u32_e32 v176, 0x420, v176
	ds_read2_b32 v[158:159], v176 offset1:132
	v_add_u32_e32 v176, 0x420, v176
	ds_read2_b32 v[160:161], v176 offset1:132
	v_add_u32_e32 v176, 0x420, v176
	ds_read2_b32 v[162:163], v176 offset1:132
	v_add_u32_e32 v176, 0x420, v176
	ds_read2_b32 v[164:165], v176 offset1:132
	v_add_u32_e32 v176, 0x420, v176
	ds_read2_b32 v[166:167], v176 offset1:132
	v_add_u32_e32 v176, 0x420, v176
	ds_read2_b32 v[168:169], v176 offset1:132
	v_add_u32_e32 v176, 0x420, v176
	ds_read2_b32 v[170:171], v176 offset1:132
	v_add_u32_e32 v176, 0x420, v176
	s_waitcnt lgkmcnt(0)
	ds_read2_b32 v[172:173], v176 offset1:132
	v_add_u32_e32 v176, 0x420, v176
	ds_read2_b32 v[174:175], v176 offset1:132
	s_waitcnt lgkmcnt(0)
	v_add_f32_e32 v112, 0, v112
	v_add_f32_e32 v113, v112, v113
	v_add_f32_e32 v114, v113, v114
	v_add_f32_e32 v115, v114, v115
	v_add_f32_e32 v116, v115, v116
	v_add_f32_e32 v117, v116, v117
	v_add_f32_e32 v118, v117, v118
	v_add_f32_e32 v119, v118, v119
	v_add_f32_e32 v120, v119, v120
	v_add_f32_e32 v121, v120, v121
	v_add_f32_e32 v122, v121, v122
	v_add_f32_e32 v123, v122, v123
	v_add_f32_e32 v124, v123, v124
	v_add_f32_e32 v125, v124, v125
	v_add_f32_e32 v126, v125, v126
	v_add_f32_e32 v127, v126, v127
	v_add_f32_e32 v128, v127, v128
	v_add_f32_e32 v129, v128, v129
	v_add_f32_e32 v130, v129, v130
	v_add_f32_e32 v131, v130, v131
	v_add_f32_e32 v132, v131, v132
	v_add_f32_e32 v133, v132, v133
	v_add_f32_e32 v134, v133, v134
	v_add_f32_e32 v135, v134, v135
	v_add_f32_e32 v136, v135, v136
	v_add_f32_e32 v137, v136, v137
	v_add_f32_e32 v138, v137, v138
	v_add_f32_e32 v139, v138, v139
	v_add_f32_e32 v140, v139, v140
	v_add_f32_e32 v141, v140, v141
	v_add_f32_e32 v142, v141, v142
	v_add_f32_e32 v143, v142, v143
	v_add_f32_e32 v144, v143, v144
	v_add_f32_e32 v145, v144, v145
	v_add_f32_e32 v146, v145, v146
	v_add_f32_e32 v147, v146, v147
	v_add_f32_e32 v148, v147, v148
	v_add_f32_e32 v149, v148, v149
	v_add_f32_e32 v150, v149, v150
	v_add_f32_e32 v151, v150, v151
	v_add_f32_e32 v152, v151, v152
	v_add_f32_e32 v153, v152, v153
	v_add_f32_e32 v154, v153, v154
	v_add_f32_e32 v155, v154, v155
	v_add_f32_e32 v156, v155, v156
	v_add_f32_e32 v157, v156, v157
	v_add_f32_e32 v158, v157, v158
	v_add_f32_e32 v159, v158, v159
	v_add_f32_e32 v160, v159, v160
	v_add_f32_e32 v161, v160, v161
	v_add_f32_e32 v162, v161, v162
	v_add_f32_e32 v163, v162, v163
	v_add_f32_e32 v164, v163, v164
	v_add_f32_e32 v165, v164, v165
	v_add_f32_e32 v166, v165, v166
	v_add_f32_e32 v167, v166, v167
	v_add_f32_e32 v168, v167, v168
	v_add_f32_e32 v169, v168, v169
	v_add_f32_e32 v170, v169, v170
	v_add_f32_e32 v171, v170, v171
	v_add_f32_e32 v172, v171, v172
	v_add_f32_e32 v173, v172, v173
	v_add_f32_e32 v174, v173, v174
	v_add_f32_e32 v175, v174, v175
	v_mov_b32_e32 v176, v3
	ds_write2_b32 v176, v112, v113 offset1:132
	v_add_u32_e32 v176, 0x420, v176
	ds_write2_b32 v176, v114, v115 offset1:132
	v_add_u32_e32 v176, 0x420, v176
	ds_write2_b32 v176, v116, v117 offset1:132
	v_add_u32_e32 v176, 0x420, v176
	ds_write2_b32 v176, v118, v119 offset1:132
	v_add_u32_e32 v176, 0x420, v176
	ds_write2_b32 v176, v120, v121 offset1:132
	v_add_u32_e32 v176, 0x420, v176
	ds_write2_b32 v176, v122, v123 offset1:132
	v_add_u32_e32 v176, 0x420, v176
	ds_write2_b32 v176, v124, v125 offset1:132
	v_add_u32_e32 v176, 0x420, v176
	ds_write2_b32 v176, v126, v127 offset1:132
	v_add_u32_e32 v176, 0x420, v176
	ds_write2_b32 v176, v128, v129 offset1:132
	v_add_u32_e32 v176, 0x420, v176
	ds_write2_b32 v176, v130, v131 offset1:132
	v_add_u32_e32 v176, 0x420, v176
	ds_write2_b32 v176, v132, v133 offset1:132
	v_add_u32_e32 v176, 0x420, v176
	ds_write2_b32 v176, v134, v135 offset1:132
	v_add_u32_e32 v176, 0x420, v176
	ds_write2_b32 v176, v136, v137 offset1:132
	v_add_u32_e32 v176, 0x420, v176
	ds_write2_b32 v176, v138, v139 offset1:132
	v_add_u32_e32 v176, 0x420, v176
	ds_write2_b32 v176, v140, v141 offset1:132
	v_add_u32_e32 v176, 0x420, v176
	s_waitcnt lgkmcnt(0)
	ds_write2_b32 v176, v142, v143 offset1:132
	v_add_u32_e32 v176, 0x420, v176
	ds_write2_b32 v176, v144, v145 offset1:132
	v_add_u32_e32 v176, 0x420, v176
	ds_write2_b32 v176, v146, v147 offset1:132
	v_add_u32_e32 v176, 0x420, v176
	ds_write2_b32 v176, v148, v149 offset1:132
	v_add_u32_e32 v176, 0x420, v176
	ds_write2_b32 v176, v150, v151 offset1:132
	v_add_u32_e32 v176, 0x420, v176
	ds_write2_b32 v176, v152, v153 offset1:132
	v_add_u32_e32 v176, 0x420, v176
	ds_write2_b32 v176, v154, v155 offset1:132
	v_add_u32_e32 v176, 0x420, v176
	ds_write2_b32 v176, v156, v157 offset1:132
	v_add_u32_e32 v176, 0x420, v176
	ds_write2_b32 v176, v158, v159 offset1:132
	v_add_u32_e32 v176, 0x420, v176
	ds_write2_b32 v176, v160, v161 offset1:132
	v_add_u32_e32 v176, 0x420, v176
	ds_write2_b32 v176, v162, v163 offset1:132
	v_add_u32_e32 v176, 0x420, v176
	ds_write2_b32 v176, v164, v165 offset1:132
	v_add_u32_e32 v176, 0x420, v176
	ds_write2_b32 v176, v166, v167 offset1:132
	v_add_u32_e32 v176, 0x420, v176
	ds_write2_b32 v176, v168, v169 offset1:132
	v_add_u32_e32 v176, 0x420, v176
	ds_write2_b32 v176, v170, v171 offset1:132
	v_add_u32_e32 v176, 0x420, v176
	s_waitcnt lgkmcnt(0)
	ds_write2_b32 v176, v172, v173 offset1:132
	v_add_u32_e32 v176, 0x420, v176
	ds_write2_b32 v176, v174, v175 offset1:132
